# L1 invalidate moved to seam arrival (issued by wave 1 after the drain barrier) instead of after the release
# speedup vs baseline: 1.0286x; 1.0286x over previous
.LBB0_800:
	s_getreg_b32 s0, hwreg(HW_REG_XCC_ID, 0, 4)
	s_waitcnt vmcnt(0)
	s_waitcnt vmcnt(0) lgkmcnt(0)
	s_barrier
	s_mov_b64 s[4:5], exec
	v_readlane_b32 s6, v255, 7
	v_readlane_b32 s7, v255, 8
	s_and_b64 s[6:7], s[4:5], s[6:7]
	s_mov_b64 exec, s[6:7]
	s_cbranch_execnz .LBB0_801
	v_readfirstlane_b32 s6, v234
	s_lshr_b32 s6, s6, 6
	s_cmp_lg_u32 s6, 1
	s_cbranch_scc1 .Lseam_skip_inv
	s_mov_b64 exec, 1
	buffer_inv sc1
	s_waitcnt vmcnt(0)

.LBB0_832:
	s_or_b64 exec, exec, s[12:13]
	s_waitcnt vmcnt(0)
	s_waitcnt vmcnt(0)

.LBB0_850:
	s_or_b64 exec, exec, s[6:7]
	s_mov_b64 s[6:7], exec
	v_mbcnt_lo_u32_b32 v1, s6, 0
	v_mbcnt_hi_u32_b32 v1, s7, v1
	v_cmp_eq_u32_e32 vcc, 0, v1
	s_waitcnt vmcnt(0)
	s_and_saveexec_b64 s[10:11], vcc
	s_cbranch_execnz .LBB0_851
	s_getpc_b64 s[98:99]
